# in-proj and gate/up K-loops: the remaining 8 VALU 64-bit address adds per iteration replaced by scalar-base loads, half-step sums formed on the scalar unit
# speedup vs baseline: 1.0031x; 1.0031x over previous
; #define PG8_STAGE(bufoff, gbase, voff) do { _Pragma("unroll") for (int _i = 0; _i < 2; ++_i) \
;         __builtin_amdgcn_global_load_lds((const unsigned*)((const char*)(gbase) + (voff)[_i]), (PG8_LAS unsigned*)(lds + (bufoff) + ldsw + _i * 8192), 16, 0, 0); } while (0)
; #define PG8_LDA(dst, b, h) do { _Pragma("unroll") for (int m = 0; m < 4; ++m) _Pragma("unroll") for (int k = 0; k < 2; ++k) dst[m][k] = *(const PG8_LAS bf16x8*)(lds + PG8_SA(b, h) + aoff + m * 2048 + k * 1024); } while (0)
; #define PG8_LDB(dst, b, h) do { _Pragma("unroll") for (int n = 0; n < 2; ++n) _Pragma("unroll") for (int k = 0; k < 2; ++k) dst[n][k] = *(const PG8_LAS bf16x8*)(lds + PG8_SB(b, h) + boff + n * 2048 + k * 1024); } while (0)
; #define PG8_MMA(ai, bj, At, Bt) do { __builtin_amdgcn_s_setprio(1); _Pragma("unroll") for (int m = 0; m < 4; ++m) _Pragma("unroll") for (int n = 0; n < 2; ++n) _Pragma("unroll") for (int k = 0; k < 2; ++k) \
;         acc[ai][bj][m][n] = __builtin_amdgcn_mfma_f32_16x16x32_bf16(Bt[n][k], At[m][k], acc[ai][bj][m][n], 0, 0, 0); __builtin_amdgcn_s_setprio(0); } while (0)
; #define PG8_WAIT_V(n) asm volatile("s_waitcnt vmcnt(" #n ")" ::: "memory")
; #define PG8_WAIT_L(n) asm volatile("s_waitcnt lgkmcnt(" #n ")" ::: "memory")
; #define PG8_BAR __builtin_amdgcn_s_barrier()
; #define PG8_SCHED __builtin_amdgcn_sched_barrier(0)
; template <class Epi, class Sched, bool ALIGN_EPI = false, bool SP2 = false>
; __device__ __forceinline__ void gemm_phase(PG8_LAS unsigned char* lds, const Gemm g, const Sched& S, const Epi& E) {
;     ...
;             PG8_LDB(B0, 0, 0); PG8_LDB(B1, 0, 1); PG8_SCHED; PG8_LDA(At, 0, 0); PG8_STAGE(PG8_SA(1, 1), a1 + hstep, voffA);
;             PG8_WAIT_V(8); PG8_WAIT_L(0); PG8_BAR; PG8_MMA(0, 0, At, B0); PG8_MMA(0, 1, At, B1); PG8_BAR; PG8_SCHED;
;             PG8_LDA(At, 0, 1); PG8_STAGE(PG8_SB(0, 0), b2, voffB); PG8_STAGE(PG8_SB(0, 1), b2 + hstep, voffB); PG8_STAGE(PG8_SA(0, 0), a2, voffA);
;             PG8_WAIT_V(8); PG8_WAIT_L(0); PG8_BAR; PG8_MMA(1, 0, At, B0); PG8_MMA(1, 1, At, B1); PG8_BAR; PG8_SCHED;
.LBB0_310:
	s_add_u32 s20, s44, 0xfff80080
	s_addc_u32 s21, s45, -1
	s_add_i32 s30, 0, 0x10000
	s_cmp_eq_u32 s56, 28
	s_cselect_b32 s47, s27, s21
	s_cselect_b32 s46, s52, s20
	v_add_u32_e32 v149, s30, v146
	s_cselect_b32 s21, s25, s55
	s_cselect_b32 s20, s53, s54
	s_add_i32 s57, 0, 0x14000
	ds_read_b128 v[142:145], v149
	ds_read_b128 v[150:153], v149 offset:1024
	ds_read_b128 v[154:157], v149 offset:2048
	ds_read_b128 v[158:161], v149 offset:3072
	v_add_u32_e32 v149, s57, v146
	ds_read_b128 v[162:165], v149
	ds_read_b128 v[166:169], v149 offset:1024
	ds_read_b128 v[170:173], v149 offset:2048
	ds_read_b128 v[174:177], v149 offset:3072
	s_add_i32 m0, s12, 0xc000
	ds_read_b128 v[178:181], v148
	ds_read_b128 v[182:185], v148 offset:1024
	ds_read_b128 v[186:189], v148 offset:2048
	ds_read_b128 v[190:193], v148 offset:3072
	ds_read_b128 v[194:197], v148 offset:4096
	ds_read_b128 v[198:201], v148 offset:5120
	ds_read_b128 v[202:205], v148 offset:6144
	ds_read_b128 v[206:209], v148 offset:7168
	global_load_lds_dwordx4 v140, s[44:45]
	s_add_i32 m0, s12, 0xe000
	s_nop 0
	global_load_lds_dwordx4 v138, s[44:45]
	s_waitcnt vmcnt(8)
	s_waitcnt lgkmcnt(0)
	s_barrier
	s_setprio 1
	s_waitcnt lgkmcnt(0)
	v_mfma_f32_16x16x32_bf16 v[128:131], v[142:145], v[178:181], v[128:131]
	v_mfma_f32_16x16x32_bf16 v[124:127], v[154:157], v[178:181], v[124:127]
	v_mfma_f32_16x16x32_bf16 v[120:123], v[142:145], v[186:189], v[120:123]
	v_mfma_f32_16x16x32_bf16 v[112:115], v[154:157], v[186:189], v[112:115]
	v_mfma_f32_16x16x32_bf16 v[104:107], v[142:145], v[194:197], v[104:107]
	v_mfma_f32_16x16x32_bf16 v[96:99], v[154:157], v[194:197], v[96:99]
	v_mfma_f32_16x16x32_bf16 v[88:91], v[142:145], v[202:205], v[88:91]
	v_mfma_f32_16x16x32_bf16 v[80:83], v[154:157], v[202:205], v[80:83]
	v_mfma_f32_16x16x32_bf16 v[128:131], v[150:153], v[182:185], v[128:131]
	v_mfma_f32_16x16x32_bf16 v[124:127], v[158:161], v[182:185], v[124:127]
	v_mfma_f32_16x16x32_bf16 v[120:123], v[150:153], v[190:193], v[120:123]
	v_mfma_f32_16x16x32_bf16 v[112:115], v[158:161], v[190:193], v[112:115]
	v_mfma_f32_16x16x32_bf16 v[104:107], v[150:153], v[198:201], v[104:107]
	v_mfma_f32_16x16x32_bf16 v[96:99], v[158:161], v[198:201], v[96:99]
	v_mfma_f32_16x16x32_bf16 v[88:91], v[150:153], v[206:209], v[88:91]
	v_mfma_f32_16x16x32_bf16 v[80:83], v[158:161], v[206:209], v[80:83]
	s_setprio 0
	s_setprio 1
	v_mfma_f32_16x16x32_bf16 v[116:119], v[162:165], v[178:181], v[116:119]
	v_mfma_f32_16x16x32_bf16 v[108:111], v[170:173], v[178:181], v[108:111]
	v_mfma_f32_16x16x32_bf16 v[100:103], v[162:165], v[186:189], v[100:103]
	v_mfma_f32_16x16x32_bf16 v[92:95], v[170:173], v[186:189], v[92:95]
	v_mfma_f32_16x16x32_bf16 v[84:87], v[162:165], v[194:197], v[84:87]
	v_mfma_f32_16x16x32_bf16 v[76:79], v[170:173], v[194:197], v[76:79]
	v_mfma_f32_16x16x32_bf16 v[72:75], v[162:165], v[202:205], v[72:75]
	v_mfma_f32_16x16x32_bf16 v[68:71], v[170:173], v[202:205], v[68:71]
	v_mfma_f32_16x16x32_bf16 v[116:119], v[166:169], v[182:185], v[116:119]
	v_mfma_f32_16x16x32_bf16 v[108:111], v[174:177], v[182:185], v[108:111]
	v_mfma_f32_16x16x32_bf16 v[100:103], v[166:169], v[190:193], v[100:103]
	v_mfma_f32_16x16x32_bf16 v[92:95], v[174:177], v[190:193], v[92:95]
	v_mfma_f32_16x16x32_bf16 v[84:87], v[166:169], v[198:201], v[84:87]
	v_mfma_f32_16x16x32_bf16 v[76:79], v[174:177], v[198:201], v[76:79]
	v_mfma_f32_16x16x32_bf16 v[72:75], v[166:169], v[206:209], v[72:75]
	v_mfma_f32_16x16x32_bf16 v[68:71], v[174:177], v[206:209], v[68:71]
	s_setprio 0
	s_barrier
	s_add_i32 s30, s30, s10
	s_mov_b32 m0, s30
	ds_read_b128 v[178:181], v148 offset:16384
	ds_read_b128 v[182:185], v148 offset:17408
	ds_read_b128 v[186:189], v148 offset:18432
	ds_read_b128 v[190:193], v148 offset:19456
	ds_read_b128 v[194:197], v148 offset:20480
	ds_read_b128 v[198:201], v148 offset:21504
	ds_read_b128 v[202:205], v148 offset:22528
	ds_read_b128 v[206:209], v148 offset:23552
	global_load_lds_dwordx4 v2, s[20:21]
	s_add_i32 m0, s30, 0x2000
	s_add_u32 s30, s20, 0x80000
	s_addc_u32 s31, s21, 0
	s_add_u32 s98, s20, s28
	s_addc_u32 s99, s21, s29
	s_add_u32 s94, s46, s28
	s_addc_u32 s95, s47, s29
	s_add_i32 s57, s57, s10
	global_load_lds_dwordx4 v132, s[20:21]
	s_mov_b32 m0, s57
	s_nop 0
	global_load_lds_dwordx4 v2, s[30:31]
	s_add_i32 m0, s57, 0x2000
	s_nop 0
	global_load_lds_dwordx4 v132, s[30:31]
	s_mov_b32 m0, s12
	s_nop 0
	global_load_lds_dwordx4 v136, s[46:47]
	s_mov_b32 m0, s13
	s_nop 0
	global_load_lds_dwordx4 v134, s[46:47]
	s_waitcnt vmcnt(8)
	s_waitcnt lgkmcnt(0)
	s_barrier
; #define PG8_STAGE(bufoff, gbase, voff) do { _Pragma("unroll") for (int _i = 0; _i < 2; ++_i) \
;         __builtin_amdgcn_global_load_lds((const unsigned*)((const char*)(gbase) + (voff)[_i]), (PG8_LAS unsigned*)(lds + (bufoff) + ldsw + _i * 8192), 16, 0, 0); } while (0)
; #define PG8_LDA(dst, b, h) do { _Pragma("unroll") for (int m = 0; m < 4; ++m) _Pragma("unroll") for (int k = 0; k < 2; ++k) dst[m][k] = *(const PG8_LAS bf16x8*)(lds + PG8_SA(b, h) + aoff + m * 2048 + k * 1024); } while (0)
; #define PG8_LDB(dst, b, h) do { _Pragma("unroll") for (int n = 0; n < 2; ++n) _Pragma("unroll") for (int k = 0; k < 2; ++k) dst[n][k] = *(const PG8_LAS bf16x8*)(lds + PG8_SB(b, h) + boff + n * 2048 + k * 1024); } while (0)
; #define PG8_MMA(ai, bj, At, Bt) do { __builtin_amdgcn_s_setprio(1); _Pragma("unroll") for (int m = 0; m < 4; ++m) _Pragma("unroll") for (int n = 0; n < 2; ++n) _Pragma("unroll") for (int k = 0; k < 2; ++k) \
;         acc[ai][bj][m][n] = __builtin_amdgcn_mfma_f32_16x16x32_bf16(Bt[n][k], At[m][k], acc[ai][bj][m][n], 0, 0, 0); __builtin_amdgcn_s_setprio(0); } while (0)
; #define PG8_WAIT_V(n) asm volatile("s_waitcnt vmcnt(" #n ")" ::: "memory")
; #define PG8_WAIT_L(n) asm volatile("s_waitcnt lgkmcnt(" #n ")" ::: "memory")
; #define PG8_BAR __builtin_amdgcn_s_barrier()
; #define PG8_SCHED __builtin_amdgcn_sched_barrier(0)
; template <class Epi, class Sched, bool ALIGN_EPI = false, bool SP2 = false>
; __device__ __forceinline__ void gemm_phase(PG8_LAS unsigned char* lds, const Gemm g, const Sched& S, const Epi& E) {
;     ...
;             PG8_WAIT_V(8); PG8_WAIT_L(0); PG8_BAR; PG8_MMA(1, 0, At, B0); PG8_MMA(1, 1, At, B1); PG8_BAR; PG8_SCHED;
;             PG8_LDB(B0, 1, 0); PG8_LDB(B1, 1, 1); PG8_SCHED; PG8_LDA(At, 1, 0); PG8_STAGE(PG8_SA(0, 1), a2 + hstep, voffA);
;             PG8_WAIT_V(8); PG8_WAIT_L(0); PG8_BAR; PG8_MMA(0, 0, At, B0); PG8_MMA(0, 1, At, B1); PG8_BAR; PG8_SCHED;
	s_setprio 1
	s_waitcnt lgkmcnt(0)
	v_mfma_f32_16x16x32_bf16 v[64:67], v[142:145], v[178:181], v[64:67]
	v_mfma_f32_16x16x32_bf16 v[60:63], v[154:157], v[178:181], v[60:63]
	v_mfma_f32_16x16x32_bf16 v[56:59], v[142:145], v[186:189], v[56:59]
	v_mfma_f32_16x16x32_bf16 v[48:51], v[154:157], v[186:189], v[48:51]
	v_mfma_f32_16x16x32_bf16 v[40:43], v[142:145], v[194:197], v[40:43]
	v_mfma_f32_16x16x32_bf16 v[32:35], v[154:157], v[194:197], v[32:35]
	v_mfma_f32_16x16x32_bf16 v[24:27], v[142:145], v[202:205], v[24:27]
	v_mfma_f32_16x16x32_bf16 v[16:19], v[154:157], v[202:205], v[16:19]
	v_mfma_f32_16x16x32_bf16 v[64:67], v[150:153], v[182:185], v[64:67]
	v_mfma_f32_16x16x32_bf16 v[60:63], v[158:161], v[182:185], v[60:63]
	v_mfma_f32_16x16x32_bf16 v[56:59], v[150:153], v[190:193], v[56:59]
	v_mfma_f32_16x16x32_bf16 v[48:51], v[158:161], v[190:193], v[48:51]
	v_mfma_f32_16x16x32_bf16 v[40:43], v[150:153], v[198:201], v[40:43]
	v_mfma_f32_16x16x32_bf16 v[32:35], v[158:161], v[198:201], v[32:35]
	v_mfma_f32_16x16x32_bf16 v[24:27], v[150:153], v[206:209], v[24:27]
	v_mfma_f32_16x16x32_bf16 v[16:19], v[158:161], v[206:209], v[16:19]
	s_setprio 0
	s_setprio 1
	v_mfma_f32_16x16x32_bf16 v[52:55], v[162:165], v[178:181], v[52:55]
	v_mfma_f32_16x16x32_bf16 v[44:47], v[170:173], v[178:181], v[44:47]
	v_mfma_f32_16x16x32_bf16 v[36:39], v[162:165], v[186:189], v[36:39]
	v_mfma_f32_16x16x32_bf16 v[28:31], v[170:173], v[186:189], v[28:31]
	v_mfma_f32_16x16x32_bf16 v[20:23], v[162:165], v[194:197], v[20:23]
	v_mfma_f32_16x16x32_bf16 v[12:15], v[170:173], v[194:197], v[12:15]
	v_mfma_f32_16x16x32_bf16 v[8:11], v[162:165], v[202:205], v[8:11]
	v_mfma_f32_16x16x32_bf16 v[4:7], v[170:173], v[202:205], v[4:7]
	v_mfma_f32_16x16x32_bf16 v[52:55], v[166:169], v[182:185], v[52:55]
	v_mfma_f32_16x16x32_bf16 v[44:47], v[174:177], v[182:185], v[44:47]
	v_mfma_f32_16x16x32_bf16 v[36:39], v[166:169], v[190:193], v[36:39]
	v_mfma_f32_16x16x32_bf16 v[28:31], v[174:177], v[190:193], v[28:31]
	v_mfma_f32_16x16x32_bf16 v[20:23], v[166:169], v[198:201], v[20:23]
	v_mfma_f32_16x16x32_bf16 v[12:15], v[174:177], v[198:201], v[12:15]
	v_mfma_f32_16x16x32_bf16 v[8:11], v[166:169], v[206:209], v[8:11]
	v_mfma_f32_16x16x32_bf16 v[4:7], v[174:177], v[206:209], v[4:7]
	s_setprio 0
	s_barrier
	s_add_i32 s57, 0, 0x18000
	v_add_u32_e32 v149, s57, v146
	s_add_i32 s58, 0, 0x1c000
	ds_read_b128 v[142:145], v149
	ds_read_b128 v[150:153], v149 offset:1024
	ds_read_b128 v[154:157], v149 offset:2048
	ds_read_b128 v[158:161], v149 offset:3072
	v_add_u32_e32 v149, s58, v146
	ds_read_b128 v[162:165], v149
	ds_read_b128 v[166:169], v149 offset:1024
	ds_read_b128 v[170:173], v149 offset:2048
	ds_read_b128 v[174:177], v149 offset:3072
	s_add_u32 s30, s46, 0x80000
	s_addc_u32 s31, s47, 0
	s_mov_b32 m0, s33
	ds_read_b128 v[178:181], v148 offset:32768
	ds_read_b128 v[182:185], v148 offset:33792
	ds_read_b128 v[186:189], v148 offset:34816
	ds_read_b128 v[190:193], v148 offset:35840
	ds_read_b128 v[194:197], v148 offset:36864
	ds_read_b128 v[198:201], v148 offset:37888
	ds_read_b128 v[202:205], v148 offset:38912
	ds_read_b128 v[206:209], v148 offset:39936
	global_load_lds_dwordx4 v136, s[30:31]
	s_mov_b32 m0, s37
	s_nop 0
	global_load_lds_dwordx4 v134, s[30:31]
	s_waitcnt vmcnt(8)
	s_waitcnt lgkmcnt(0)
	s_barrier
	s_setprio 1
	s_waitcnt lgkmcnt(0)
	v_mfma_f32_16x16x32_bf16 v[128:131], v[142:145], v[178:181], v[128:131]
	v_mfma_f32_16x16x32_bf16 v[124:127], v[154:157], v[178:181], v[124:127]
	v_mfma_f32_16x16x32_bf16 v[120:123], v[142:145], v[186:189], v[120:123]
	v_mfma_f32_16x16x32_bf16 v[112:115], v[154:157], v[186:189], v[112:115]
	v_mfma_f32_16x16x32_bf16 v[104:107], v[142:145], v[194:197], v[104:107]
	v_mfma_f32_16x16x32_bf16 v[96:99], v[154:157], v[194:197], v[96:99]
	v_mfma_f32_16x16x32_bf16 v[88:91], v[142:145], v[202:205], v[88:91]
	v_mfma_f32_16x16x32_bf16 v[80:83], v[154:157], v[202:205], v[80:83]
	v_mfma_f32_16x16x32_bf16 v[128:131], v[150:153], v[182:185], v[128:131]
	v_mfma_f32_16x16x32_bf16 v[124:127], v[158:161], v[182:185], v[124:127]
	v_mfma_f32_16x16x32_bf16 v[120:123], v[150:153], v[190:193], v[120:123]
	v_mfma_f32_16x16x32_bf16 v[112:115], v[158:161], v[190:193], v[112:115]
	v_mfma_f32_16x16x32_bf16 v[104:107], v[150:153], v[198:201], v[104:107]
	v_mfma_f32_16x16x32_bf16 v[96:99], v[158:161], v[198:201], v[96:99]
	v_mfma_f32_16x16x32_bf16 v[88:91], v[150:153], v[206:209], v[88:91]
	v_mfma_f32_16x16x32_bf16 v[80:83], v[158:161], v[206:209], v[80:83]
	s_setprio 0
	s_setprio 1
	v_mfma_f32_16x16x32_bf16 v[116:119], v[162:165], v[178:181], v[116:119]
	v_mfma_f32_16x16x32_bf16 v[108:111], v[170:173], v[178:181], v[108:111]
	v_mfma_f32_16x16x32_bf16 v[100:103], v[162:165], v[186:189], v[100:103]
	v_mfma_f32_16x16x32_bf16 v[92:95], v[170:173], v[186:189], v[92:95]
	v_mfma_f32_16x16x32_bf16 v[84:87], v[162:165], v[194:197], v[84:87]
	v_mfma_f32_16x16x32_bf16 v[76:79], v[170:173], v[194:197], v[76:79]
	v_mfma_f32_16x16x32_bf16 v[72:75], v[162:165], v[202:205], v[72:75]
	v_mfma_f32_16x16x32_bf16 v[68:71], v[170:173], v[202:205], v[68:71]
	v_mfma_f32_16x16x32_bf16 v[116:119], v[166:169], v[182:185], v[116:119]
	v_mfma_f32_16x16x32_bf16 v[108:111], v[174:177], v[182:185], v[108:111]
	v_mfma_f32_16x16x32_bf16 v[100:103], v[166:169], v[190:193], v[100:103]
	v_mfma_f32_16x16x32_bf16 v[92:95], v[174:177], v[190:193], v[92:95]
	v_mfma_f32_16x16x32_bf16 v[84:87], v[166:169], v[198:201], v[84:87]
	v_mfma_f32_16x16x32_bf16 v[76:79], v[174:177], v[198:201], v[76:79]
	v_mfma_f32_16x16x32_bf16 v[72:75], v[166:169], v[206:209], v[72:75]
	v_mfma_f32_16x16x32_bf16 v[68:71], v[174:177], v[206:209], v[68:71]
	s_setprio 0
	s_barrier
; #define PG8_STAGE(bufoff, gbase, voff) do { _Pragma("unroll") for (int _i = 0; _i < 2; ++_i) \
;         __builtin_amdgcn_global_load_lds((const unsigned*)((const char*)(gbase) + (voff)[_i]), (PG8_LAS unsigned*)(lds + (bufoff) + ldsw + _i * 8192), 16, 0, 0); } while (0)
; #define PG8_LDA(dst, b, h) do { _Pragma("unroll") for (int m = 0; m < 4; ++m) _Pragma("unroll") for (int k = 0; k < 2; ++k) dst[m][k] = *(const PG8_LAS bf16x8*)(lds + PG8_SA(b, h) + aoff + m * 2048 + k * 1024); } while (0)
; #define PG8_MMA(ai, bj, At, Bt) do { __builtin_amdgcn_s_setprio(1); _Pragma("unroll") for (int m = 0; m < 4; ++m) _Pragma("unroll") for (int n = 0; n < 2; ++n) _Pragma("unroll") for (int k = 0; k < 2; ++k) \
;         acc[ai][bj][m][n] = __builtin_amdgcn_mfma_f32_16x16x32_bf16(Bt[n][k], At[m][k], acc[ai][bj][m][n], 0, 0, 0); __builtin_amdgcn_s_setprio(0); } while (0)
; #define PG8_WAIT_V(n) asm volatile("s_waitcnt vmcnt(" #n ")" ::: "memory")
; #define PG8_WAIT_L(n) asm volatile("s_waitcnt lgkmcnt(" #n ")" ::: "memory")
; #define PG8_BAR __builtin_amdgcn_s_barrier()
; #define PG8_SCHED __builtin_amdgcn_sched_barrier(0)
; template <class Epi, class Sched, bool ALIGN_EPI = false, bool SP2 = false>
; __device__ __forceinline__ void gemm_phase(PG8_LAS unsigned char* lds, const Gemm g, const Sched& S, const Epi& E) {
;     ...
;             PG8_LDA(At, 1, 1); PG8_STAGE(PG8_SB(1, 0), b3, voffB); PG8_STAGE(PG8_SB(1, 1), b3 + hstep, voffB); PG8_STAGE(PG8_SA(1, 0), a3, voffA);
;             PG8_WAIT_V(8); PG8_WAIT_L(0); PG8_BAR; PG8_MMA(1, 0, At, B0); PG8_MMA(1, 1, At, B1); PG8_BAR; PG8_SCHED;
;     ...
;         if constexpr (ALIGN_EPI) { if (wr == 0) PG8_BAR; }
	s_add_i32 s30, s57, s10
	s_mov_b32 m0, s30
	ds_read_b128 v[178:181], v148 offset:49152
	ds_read_b128 v[182:185], v148 offset:50176
	ds_read_b128 v[186:189], v148 offset:51200
	ds_read_b128 v[190:193], v148 offset:52224
	ds_read_b128 v[194:197], v148 offset:53248
	ds_read_b128 v[198:201], v148 offset:54272
	ds_read_b128 v[202:205], v148 offset:55296
	ds_read_b128 v[206:209], v148 offset:56320
	global_load_lds_dwordx4 v2, s[98:99]
	s_add_i32 m0, s30, 0x2000
	s_add_u32 s20, s20, 0x80080
	s_addc_u32 s21, s21, 0
	s_add_i32 s30, s58, s10
	global_load_lds_dwordx4 v132, s[98:99]
	s_mov_b32 m0, s30
	s_nop 0
	global_load_lds_dwordx4 v2, s[20:21]
	s_add_i32 m0, s30, 0x2000
	s_nop 0
	global_load_lds_dwordx4 v132, s[20:21]
	s_mov_b32 m0, s18
	s_nop 0
	global_load_lds_dwordx4 v136, s[94:95]
	s_mov_b32 m0, s48
	s_nop 0
	global_load_lds_dwordx4 v134, s[94:95]
	s_waitcnt vmcnt(8)
	s_waitcnt lgkmcnt(0)
	s_barrier
	s_setprio 1
	s_waitcnt lgkmcnt(0)
	v_mfma_f32_16x16x32_bf16 v[64:67], v[142:145], v[178:181], v[64:67]
	v_mfma_f32_16x16x32_bf16 v[60:63], v[154:157], v[178:181], v[60:63]
	v_mfma_f32_16x16x32_bf16 v[56:59], v[142:145], v[186:189], v[56:59]
	v_mfma_f32_16x16x32_bf16 v[48:51], v[154:157], v[186:189], v[48:51]
	v_mfma_f32_16x16x32_bf16 v[40:43], v[142:145], v[194:197], v[40:43]
	v_mfma_f32_16x16x32_bf16 v[32:35], v[154:157], v[194:197], v[32:35]
	v_mfma_f32_16x16x32_bf16 v[24:27], v[142:145], v[202:205], v[24:27]
	v_mfma_f32_16x16x32_bf16 v[16:19], v[154:157], v[202:205], v[16:19]
	v_mfma_f32_16x16x32_bf16 v[64:67], v[150:153], v[182:185], v[64:67]
	v_mfma_f32_16x16x32_bf16 v[60:63], v[158:161], v[182:185], v[60:63]
	v_mfma_f32_16x16x32_bf16 v[56:59], v[150:153], v[190:193], v[56:59]
	v_mfma_f32_16x16x32_bf16 v[48:51], v[158:161], v[190:193], v[48:51]
	v_mfma_f32_16x16x32_bf16 v[40:43], v[150:153], v[198:201], v[40:43]
	v_mfma_f32_16x16x32_bf16 v[32:35], v[158:161], v[198:201], v[32:35]
	v_mfma_f32_16x16x32_bf16 v[24:27], v[150:153], v[206:209], v[24:27]
	v_mfma_f32_16x16x32_bf16 v[16:19], v[158:161], v[206:209], v[16:19]
	s_setprio 0
	s_setprio 1
	v_mfma_f32_16x16x32_bf16 v[52:55], v[162:165], v[178:181], v[52:55]
	v_mfma_f32_16x16x32_bf16 v[44:47], v[170:173], v[178:181], v[44:47]
	v_mfma_f32_16x16x32_bf16 v[36:39], v[162:165], v[186:189], v[36:39]
	v_mfma_f32_16x16x32_bf16 v[28:31], v[170:173], v[186:189], v[28:31]
	v_mfma_f32_16x16x32_bf16 v[20:23], v[162:165], v[194:197], v[20:23]
	v_mfma_f32_16x16x32_bf16 v[12:15], v[170:173], v[194:197], v[12:15]
	v_mfma_f32_16x16x32_bf16 v[8:11], v[162:165], v[202:205], v[8:11]
	v_mfma_f32_16x16x32_bf16 v[4:7], v[170:173], v[202:205], v[4:7]
	v_mfma_f32_16x16x32_bf16 v[52:55], v[166:169], v[182:185], v[52:55]
	v_mfma_f32_16x16x32_bf16 v[44:47], v[174:177], v[182:185], v[44:47]
	v_mfma_f32_16x16x32_bf16 v[36:39], v[166:169], v[190:193], v[36:39]
	v_mfma_f32_16x16x32_bf16 v[28:31], v[174:177], v[190:193], v[28:31]
	v_mfma_f32_16x16x32_bf16 v[20:23], v[166:169], v[198:201], v[20:23]
	v_mfma_f32_16x16x32_bf16 v[12:15], v[174:177], v[198:201], v[12:15]
	v_mfma_f32_16x16x32_bf16 v[8:11], v[166:169], v[206:209], v[8:11]
	v_mfma_f32_16x16x32_bf16 v[4:7], v[174:177], v[206:209], v[4:7]
	s_setprio 0
	s_barrier
	s_add_i32 s56, s56, 2
	s_add_u32 s54, s54, 0x100
	s_addc_u32 s55, s55, 0
	s_add_u32 s44, s44, 0x100
	s_addc_u32 s45, s45, 0
	s_cmp_gt_u32 s56, 29
	s_cbranch_scc0 .LBB0_310
	s_and_b64 vcc, exec, s[22:23]
	s_cbranch_vccz .LBB0_313
	s_barrier

; #define PG8_STAGE(bufoff, gbase, voff) do { _Pragma("unroll") for (int _i = 0; _i < 2; ++_i) \
;         __builtin_amdgcn_global_load_lds((const unsigned*)((const char*)(gbase) + (voff)[_i]), (PG8_LAS unsigned*)(lds + (bufoff) + ldsw + _i * 8192), 16, 0, 0); } while (0)
; #define PG8_LDA(dst, b, h) do { _Pragma("unroll") for (int m = 0; m < 4; ++m) _Pragma("unroll") for (int k = 0; k < 2; ++k) dst[m][k] = *(const PG8_LAS bf16x8*)(lds + PG8_SA(b, h) + aoff + m * 2048 + k * 1024); } while (0)
; #define PG8_LDB(dst, b, h) do { _Pragma("unroll") for (int n = 0; n < 2; ++n) _Pragma("unroll") for (int k = 0; k < 2; ++k) dst[n][k] = *(const PG8_LAS bf16x8*)(lds + PG8_SB(b, h) + boff + n * 2048 + k * 1024); } while (0)
; #define PG8_MMA(ai, bj, At, Bt) do { __builtin_amdgcn_s_setprio(1); _Pragma("unroll") for (int m = 0; m < 4; ++m) _Pragma("unroll") for (int n = 0; n < 2; ++n) _Pragma("unroll") for (int k = 0; k < 2; ++k) \
;         acc[ai][bj][m][n] = __builtin_amdgcn_mfma_f32_16x16x32_bf16(Bt[n][k], At[m][k], acc[ai][bj][m][n], 0, 0, 0); __builtin_amdgcn_s_setprio(0); } while (0)
; #define PG8_WAIT_V(n) asm volatile("s_waitcnt vmcnt(" #n ")" ::: "memory")
; #define PG8_WAIT_L(n) asm volatile("s_waitcnt lgkmcnt(" #n ")" ::: "memory")
; #define PG8_BAR __builtin_amdgcn_s_barrier()
; #define PG8_SCHED __builtin_amdgcn_sched_barrier(0)
; template <class Epi, class Sched, bool ALIGN_EPI = false, bool SP2 = false>
; __device__ __forceinline__ void gemm_phase(PG8_LAS unsigned char* lds, const Gemm g, const Sched& S, const Epi& E) {
;     ...
;             PG8_LDB(B0, 0, 0); PG8_LDB(B1, 0, 1); PG8_SCHED; PG8_LDA(At, 0, 0); PG8_STAGE(PG8_SA(1, 1), a1 + hstep, voffA);
;             PG8_WAIT_V(8); PG8_WAIT_L(0); PG8_BAR; PG8_MMA(0, 0, At, B0); PG8_MMA(0, 1, At, B1); PG8_BAR; PG8_SCHED;
;             PG8_LDA(At, 0, 1); PG8_STAGE(PG8_SB(0, 0), b2, voffB); PG8_STAGE(PG8_SB(0, 1), b2 + hstep, voffB); PG8_STAGE(PG8_SA(0, 0), a2, voffA);
;             PG8_WAIT_V(8); PG8_WAIT_L(0); PG8_BAR; PG8_MMA(1, 0, At, B0); PG8_MMA(1, 1, At, B1); PG8_BAR; PG8_SCHED;
.LBB0_2165:
	s_add_u32 s20, s44, 0xfff80080
	s_addc_u32 s21, s45, -1
	s_add_i32 s30, 0, 0x10000
	s_cmp_eq_u32 s56, 28
	s_cselect_b32 s47, s12, s21
	s_cselect_b32 s46, s13, s20
	v_add_u32_e32 v149, s30, v146
	s_cselect_b32 s21, s25, s55
	s_cselect_b32 s20, s27, s33
	s_add_i32 s57, 0, 0x14000
	ds_read_b128 v[142:145], v149
	ds_read_b128 v[150:153], v149 offset:1024
	ds_read_b128 v[154:157], v149 offset:2048
	ds_read_b128 v[158:161], v149 offset:3072
	v_add_u32_e32 v149, s57, v146
	ds_read_b128 v[162:165], v149
	ds_read_b128 v[166:169], v149 offset:1024
	ds_read_b128 v[170:173], v149 offset:2048
	ds_read_b128 v[174:177], v149 offset:3072
	s_add_i32 m0, s43, 0xc000
	ds_read_b128 v[178:181], v148
	ds_read_b128 v[182:185], v148 offset:1024
	ds_read_b128 v[186:189], v148 offset:2048
	ds_read_b128 v[190:193], v148 offset:3072
	ds_read_b128 v[194:197], v148 offset:4096
	ds_read_b128 v[198:201], v148 offset:5120
	ds_read_b128 v[202:205], v148 offset:6144
	ds_read_b128 v[206:209], v148 offset:7168
	global_load_lds_dwordx4 v140, s[44:45]
	s_add_i32 m0, s43, 0xe000
	s_nop 0
	global_load_lds_dwordx4 v138, s[44:45]
	s_waitcnt vmcnt(8)
	s_waitcnt lgkmcnt(0)
	s_barrier
	s_setprio 1
	s_waitcnt lgkmcnt(0)
	v_mfma_f32_16x16x32_bf16 v[128:131], v[142:145], v[178:181], v[128:131]
	v_mfma_f32_16x16x32_bf16 v[120:123], v[154:157], v[178:181], v[120:123]
	v_mfma_f32_16x16x32_bf16 v[112:115], v[142:145], v[186:189], v[112:115]
	v_mfma_f32_16x16x32_bf16 v[104:107], v[154:157], v[186:189], v[104:107]
	v_mfma_f32_16x16x32_bf16 v[96:99], v[142:145], v[194:197], v[96:99]
	v_mfma_f32_16x16x32_bf16 v[88:91], v[154:157], v[194:197], v[88:91]
	v_mfma_f32_16x16x32_bf16 v[80:83], v[142:145], v[202:205], v[80:83]
	v_mfma_f32_16x16x32_bf16 v[72:75], v[154:157], v[202:205], v[72:75]
	v_mfma_f32_16x16x32_bf16 v[128:131], v[150:153], v[182:185], v[128:131]
	v_mfma_f32_16x16x32_bf16 v[120:123], v[158:161], v[182:185], v[120:123]
	v_mfma_f32_16x16x32_bf16 v[112:115], v[150:153], v[190:193], v[112:115]
	v_mfma_f32_16x16x32_bf16 v[104:107], v[158:161], v[190:193], v[104:107]
	v_mfma_f32_16x16x32_bf16 v[96:99], v[150:153], v[198:201], v[96:99]
	v_mfma_f32_16x16x32_bf16 v[88:91], v[158:161], v[198:201], v[88:91]
	v_mfma_f32_16x16x32_bf16 v[80:83], v[150:153], v[206:209], v[80:83]
	v_mfma_f32_16x16x32_bf16 v[72:75], v[158:161], v[206:209], v[72:75]
	s_setprio 0
	s_setprio 1
	v_mfma_f32_16x16x32_bf16 v[124:127], v[162:165], v[178:181], v[124:127]
	v_mfma_f32_16x16x32_bf16 v[116:119], v[170:173], v[178:181], v[116:119]
	v_mfma_f32_16x16x32_bf16 v[108:111], v[162:165], v[186:189], v[108:111]
	v_mfma_f32_16x16x32_bf16 v[100:103], v[170:173], v[186:189], v[100:103]
	v_mfma_f32_16x16x32_bf16 v[92:95], v[162:165], v[194:197], v[92:95]
	v_mfma_f32_16x16x32_bf16 v[84:87], v[170:173], v[194:197], v[84:87]
	v_mfma_f32_16x16x32_bf16 v[76:79], v[162:165], v[202:205], v[76:79]
	v_mfma_f32_16x16x32_bf16 v[68:71], v[170:173], v[202:205], v[68:71]
	v_mfma_f32_16x16x32_bf16 v[124:127], v[166:169], v[182:185], v[124:127]
	v_mfma_f32_16x16x32_bf16 v[116:119], v[174:177], v[182:185], v[116:119]
	v_mfma_f32_16x16x32_bf16 v[108:111], v[166:169], v[190:193], v[108:111]
	v_mfma_f32_16x16x32_bf16 v[100:103], v[174:177], v[190:193], v[100:103]
	v_mfma_f32_16x16x32_bf16 v[92:95], v[166:169], v[198:201], v[92:95]
	v_mfma_f32_16x16x32_bf16 v[84:87], v[174:177], v[198:201], v[84:87]
	v_mfma_f32_16x16x32_bf16 v[76:79], v[166:169], v[206:209], v[76:79]
	v_mfma_f32_16x16x32_bf16 v[68:71], v[174:177], v[206:209], v[68:71]
	s_setprio 0
	s_barrier
	s_add_i32 s30, s30, s11
	s_mov_b32 m0, s30
	ds_read_b128 v[178:181], v148 offset:16384
	ds_read_b128 v[182:185], v148 offset:17408
	ds_read_b128 v[186:189], v148 offset:18432
	ds_read_b128 v[190:193], v148 offset:19456
	ds_read_b128 v[194:197], v148 offset:20480
	ds_read_b128 v[198:201], v148 offset:21504
	ds_read_b128 v[202:205], v148 offset:22528
	ds_read_b128 v[206:209], v148 offset:23552
	global_load_lds_dwordx4 v2, s[20:21]
	s_add_i32 m0, s30, 0x2000
	s_add_u32 s30, s20, 0x80000
	s_addc_u32 s31, s21, 0
	s_add_u32 s98, s20, s28
	s_addc_u32 s99, s21, s29
	s_add_u32 s94, s46, s28
	s_addc_u32 s95, s47, s29
	s_add_i32 s57, s57, s11
	global_load_lds_dwordx4 v132, s[20:21]
	s_mov_b32 m0, s57
	s_nop 0
	global_load_lds_dwordx4 v2, s[30:31]
	s_add_i32 m0, s57, 0x2000
	s_nop 0
	global_load_lds_dwordx4 v132, s[30:31]
	s_mov_b32 m0, s43
	s_nop 0
	global_load_lds_dwordx4 v136, s[46:47]
	s_mov_b32 m0, s49
	s_nop 0
	global_load_lds_dwordx4 v134, s[46:47]
	s_waitcnt vmcnt(8)
	s_waitcnt lgkmcnt(0)
	s_barrier
; #define PG8_STAGE(bufoff, gbase, voff) do { _Pragma("unroll") for (int _i = 0; _i < 2; ++_i) \
;         __builtin_amdgcn_global_load_lds((const unsigned*)((const char*)(gbase) + (voff)[_i]), (PG8_LAS unsigned*)(lds + (bufoff) + ldsw + _i * 8192), 16, 0, 0); } while (0)
; #define PG8_LDA(dst, b, h) do { _Pragma("unroll") for (int m = 0; m < 4; ++m) _Pragma("unroll") for (int k = 0; k < 2; ++k) dst[m][k] = *(const PG8_LAS bf16x8*)(lds + PG8_SA(b, h) + aoff + m * 2048 + k * 1024); } while (0)
; #define PG8_LDB(dst, b, h) do { _Pragma("unroll") for (int n = 0; n < 2; ++n) _Pragma("unroll") for (int k = 0; k < 2; ++k) dst[n][k] = *(const PG8_LAS bf16x8*)(lds + PG8_SB(b, h) + boff + n * 2048 + k * 1024); } while (0)
; #define PG8_MMA(ai, bj, At, Bt) do { __builtin_amdgcn_s_setprio(1); _Pragma("unroll") for (int m = 0; m < 4; ++m) _Pragma("unroll") for (int n = 0; n < 2; ++n) _Pragma("unroll") for (int k = 0; k < 2; ++k) \
;         acc[ai][bj][m][n] = __builtin_amdgcn_mfma_f32_16x16x32_bf16(Bt[n][k], At[m][k], acc[ai][bj][m][n], 0, 0, 0); __builtin_amdgcn_s_setprio(0); } while (0)
; #define PG8_WAIT_V(n) asm volatile("s_waitcnt vmcnt(" #n ")" ::: "memory")
; #define PG8_WAIT_L(n) asm volatile("s_waitcnt lgkmcnt(" #n ")" ::: "memory")
; #define PG8_BAR __builtin_amdgcn_s_barrier()
; #define PG8_SCHED __builtin_amdgcn_sched_barrier(0)
; template <class Epi, class Sched, bool ALIGN_EPI = false, bool SP2 = false>
; __device__ __forceinline__ void gemm_phase(PG8_LAS unsigned char* lds, const Gemm g, const Sched& S, const Epi& E) {
;     ...
;             PG8_WAIT_V(8); PG8_WAIT_L(0); PG8_BAR; PG8_MMA(1, 0, At, B0); PG8_MMA(1, 1, At, B1); PG8_BAR; PG8_SCHED;
;             PG8_LDB(B0, 1, 0); PG8_LDB(B1, 1, 1); PG8_SCHED; PG8_LDA(At, 1, 0); PG8_STAGE(PG8_SA(0, 1), a2 + hstep, voffA);
;             PG8_WAIT_V(8); PG8_WAIT_L(0); PG8_BAR; PG8_MMA(0, 0, At, B0); PG8_MMA(0, 1, At, B1); PG8_BAR; PG8_SCHED;
	s_setprio 1
	s_waitcnt lgkmcnt(0)
	v_mfma_f32_16x16x32_bf16 v[64:67], v[142:145], v[178:181], v[64:67]
	v_mfma_f32_16x16x32_bf16 v[56:59], v[154:157], v[178:181], v[56:59]
	v_mfma_f32_16x16x32_bf16 v[48:51], v[142:145], v[186:189], v[48:51]
	v_mfma_f32_16x16x32_bf16 v[40:43], v[154:157], v[186:189], v[40:43]
	v_mfma_f32_16x16x32_bf16 v[32:35], v[142:145], v[194:197], v[32:35]
	v_mfma_f32_16x16x32_bf16 v[24:27], v[154:157], v[194:197], v[24:27]
	v_mfma_f32_16x16x32_bf16 v[16:19], v[142:145], v[202:205], v[16:19]
	v_mfma_f32_16x16x32_bf16 v[8:11], v[154:157], v[202:205], v[8:11]
	v_mfma_f32_16x16x32_bf16 v[64:67], v[150:153], v[182:185], v[64:67]
	v_mfma_f32_16x16x32_bf16 v[56:59], v[158:161], v[182:185], v[56:59]
	v_mfma_f32_16x16x32_bf16 v[48:51], v[150:153], v[190:193], v[48:51]
	v_mfma_f32_16x16x32_bf16 v[40:43], v[158:161], v[190:193], v[40:43]
	v_mfma_f32_16x16x32_bf16 v[32:35], v[150:153], v[198:201], v[32:35]
	v_mfma_f32_16x16x32_bf16 v[24:27], v[158:161], v[198:201], v[24:27]
	v_mfma_f32_16x16x32_bf16 v[16:19], v[150:153], v[206:209], v[16:19]
	v_mfma_f32_16x16x32_bf16 v[8:11], v[158:161], v[206:209], v[8:11]
	s_setprio 0
	s_setprio 1
	v_mfma_f32_16x16x32_bf16 v[60:63], v[162:165], v[178:181], v[60:63]
	v_mfma_f32_16x16x32_bf16 v[52:55], v[170:173], v[178:181], v[52:55]
	v_mfma_f32_16x16x32_bf16 v[44:47], v[162:165], v[186:189], v[44:47]
	v_mfma_f32_16x16x32_bf16 v[36:39], v[170:173], v[186:189], v[36:39]
	v_mfma_f32_16x16x32_bf16 v[28:31], v[162:165], v[194:197], v[28:31]
	v_mfma_f32_16x16x32_bf16 v[20:23], v[170:173], v[194:197], v[20:23]
	v_mfma_f32_16x16x32_bf16 v[12:15], v[162:165], v[202:205], v[12:15]
	v_mfma_f32_16x16x32_bf16 v[4:7], v[170:173], v[202:205], v[4:7]
	v_mfma_f32_16x16x32_bf16 v[60:63], v[166:169], v[182:185], v[60:63]
	v_mfma_f32_16x16x32_bf16 v[52:55], v[174:177], v[182:185], v[52:55]
	v_mfma_f32_16x16x32_bf16 v[44:47], v[166:169], v[190:193], v[44:47]
	v_mfma_f32_16x16x32_bf16 v[36:39], v[174:177], v[190:193], v[36:39]
	v_mfma_f32_16x16x32_bf16 v[28:31], v[166:169], v[198:201], v[28:31]
	v_mfma_f32_16x16x32_bf16 v[20:23], v[174:177], v[198:201], v[20:23]
	v_mfma_f32_16x16x32_bf16 v[12:15], v[166:169], v[206:209], v[12:15]
	v_mfma_f32_16x16x32_bf16 v[4:7], v[174:177], v[206:209], v[4:7]
	s_setprio 0
	s_barrier
	s_add_i32 s57, 0, 0x18000
	v_add_u32_e32 v149, s57, v146
	s_add_i32 s58, 0, 0x1c000
	ds_read_b128 v[142:145], v149
	ds_read_b128 v[150:153], v149 offset:1024
	ds_read_b128 v[154:157], v149 offset:2048
	ds_read_b128 v[158:161], v149 offset:3072
	v_add_u32_e32 v149, s58, v146
	ds_read_b128 v[162:165], v149
	ds_read_b128 v[166:169], v149 offset:1024
	ds_read_b128 v[170:173], v149 offset:2048
	ds_read_b128 v[174:177], v149 offset:3072
	s_add_u32 s30, s46, 0x80000
	s_addc_u32 s31, s47, 0
	s_mov_b32 m0, s50
	ds_read_b128 v[178:181], v148 offset:32768
	ds_read_b128 v[182:185], v148 offset:33792
	ds_read_b128 v[186:189], v148 offset:34816
	ds_read_b128 v[190:193], v148 offset:35840
	ds_read_b128 v[194:197], v148 offset:36864
	ds_read_b128 v[198:201], v148 offset:37888
	ds_read_b128 v[202:205], v148 offset:38912
	ds_read_b128 v[206:209], v148 offset:39936
	global_load_lds_dwordx4 v136, s[30:31]
	s_mov_b32 m0, s51
	s_nop 0
	global_load_lds_dwordx4 v134, s[30:31]
	s_waitcnt vmcnt(8)
	s_waitcnt lgkmcnt(0)
	s_barrier
	s_setprio 1
	s_waitcnt lgkmcnt(0)
	v_mfma_f32_16x16x32_bf16 v[128:131], v[142:145], v[178:181], v[128:131]
	v_mfma_f32_16x16x32_bf16 v[120:123], v[154:157], v[178:181], v[120:123]
	v_mfma_f32_16x16x32_bf16 v[112:115], v[142:145], v[186:189], v[112:115]
	v_mfma_f32_16x16x32_bf16 v[104:107], v[154:157], v[186:189], v[104:107]
	v_mfma_f32_16x16x32_bf16 v[96:99], v[142:145], v[194:197], v[96:99]
	v_mfma_f32_16x16x32_bf16 v[88:91], v[154:157], v[194:197], v[88:91]
	v_mfma_f32_16x16x32_bf16 v[80:83], v[142:145], v[202:205], v[80:83]
	v_mfma_f32_16x16x32_bf16 v[72:75], v[154:157], v[202:205], v[72:75]
	v_mfma_f32_16x16x32_bf16 v[128:131], v[150:153], v[182:185], v[128:131]
	v_mfma_f32_16x16x32_bf16 v[120:123], v[158:161], v[182:185], v[120:123]
	v_mfma_f32_16x16x32_bf16 v[112:115], v[150:153], v[190:193], v[112:115]
	v_mfma_f32_16x16x32_bf16 v[104:107], v[158:161], v[190:193], v[104:107]
	v_mfma_f32_16x16x32_bf16 v[96:99], v[150:153], v[198:201], v[96:99]
	v_mfma_f32_16x16x32_bf16 v[88:91], v[158:161], v[198:201], v[88:91]
	v_mfma_f32_16x16x32_bf16 v[80:83], v[150:153], v[206:209], v[80:83]
	v_mfma_f32_16x16x32_bf16 v[72:75], v[158:161], v[206:209], v[72:75]
	s_setprio 0
	s_setprio 1
	v_mfma_f32_16x16x32_bf16 v[124:127], v[162:165], v[178:181], v[124:127]
	v_mfma_f32_16x16x32_bf16 v[116:119], v[170:173], v[178:181], v[116:119]
	v_mfma_f32_16x16x32_bf16 v[108:111], v[162:165], v[186:189], v[108:111]
	v_mfma_f32_16x16x32_bf16 v[100:103], v[170:173], v[186:189], v[100:103]
	v_mfma_f32_16x16x32_bf16 v[92:95], v[162:165], v[194:197], v[92:95]
	v_mfma_f32_16x16x32_bf16 v[84:87], v[170:173], v[194:197], v[84:87]
	v_mfma_f32_16x16x32_bf16 v[76:79], v[162:165], v[202:205], v[76:79]
	v_mfma_f32_16x16x32_bf16 v[68:71], v[170:173], v[202:205], v[68:71]
	v_mfma_f32_16x16x32_bf16 v[124:127], v[166:169], v[182:185], v[124:127]
	v_mfma_f32_16x16x32_bf16 v[116:119], v[174:177], v[182:185], v[116:119]
	v_mfma_f32_16x16x32_bf16 v[108:111], v[166:169], v[190:193], v[108:111]
	v_mfma_f32_16x16x32_bf16 v[100:103], v[174:177], v[190:193], v[100:103]
	v_mfma_f32_16x16x32_bf16 v[92:95], v[166:169], v[198:201], v[92:95]
	v_mfma_f32_16x16x32_bf16 v[84:87], v[174:177], v[198:201], v[84:87]
	v_mfma_f32_16x16x32_bf16 v[76:79], v[166:169], v[206:209], v[76:79]
	v_mfma_f32_16x16x32_bf16 v[68:71], v[174:177], v[206:209], v[68:71]
	s_setprio 0
	s_barrier
; #define PG8_STAGE(bufoff, gbase, voff) do { _Pragma("unroll") for (int _i = 0; _i < 2; ++_i) \
;         __builtin_amdgcn_global_load_lds((const unsigned*)((const char*)(gbase) + (voff)[_i]), (PG8_LAS unsigned*)(lds + (bufoff) + ldsw + _i * 8192), 16, 0, 0); } while (0)
; #define PG8_LDA(dst, b, h) do { _Pragma("unroll") for (int m = 0; m < 4; ++m) _Pragma("unroll") for (int k = 0; k < 2; ++k) dst[m][k] = *(const PG8_LAS bf16x8*)(lds + PG8_SA(b, h) + aoff + m * 2048 + k * 1024); } while (0)
; #define PG8_MMA(ai, bj, At, Bt) do { __builtin_amdgcn_s_setprio(1); _Pragma("unroll") for (int m = 0; m < 4; ++m) _Pragma("unroll") for (int n = 0; n < 2; ++n) _Pragma("unroll") for (int k = 0; k < 2; ++k) \
;         acc[ai][bj][m][n] = __builtin_amdgcn_mfma_f32_16x16x32_bf16(Bt[n][k], At[m][k], acc[ai][bj][m][n], 0, 0, 0); __builtin_amdgcn_s_setprio(0); } while (0)
; #define PG8_WAIT_V(n) asm volatile("s_waitcnt vmcnt(" #n ")" ::: "memory")
; #define PG8_WAIT_L(n) asm volatile("s_waitcnt lgkmcnt(" #n ")" ::: "memory")
; #define PG8_BAR __builtin_amdgcn_s_barrier()
; #define PG8_SCHED __builtin_amdgcn_sched_barrier(0)
; template <class Epi, class Sched, bool ALIGN_EPI = false, bool SP2 = false>
; __device__ __forceinline__ void gemm_phase(PG8_LAS unsigned char* lds, const Gemm g, const Sched& S, const Epi& E) {
;     ...
;             PG8_LDA(At, 1, 1); PG8_STAGE(PG8_SB(1, 0), b3, voffB); PG8_STAGE(PG8_SB(1, 1), b3 + hstep, voffB); PG8_STAGE(PG8_SA(1, 0), a3, voffA);
;             PG8_WAIT_V(8); PG8_WAIT_L(0); PG8_BAR; PG8_MMA(1, 0, At, B0); PG8_MMA(1, 1, At, B1); PG8_BAR; PG8_SCHED;
;     ...
;         if constexpr (ALIGN_EPI) { if (wr == 0) PG8_BAR; }
	s_add_i32 s30, s57, s11
	s_mov_b32 m0, s30
	ds_read_b128 v[178:181], v148 offset:49152
	ds_read_b128 v[182:185], v148 offset:50176
	ds_read_b128 v[186:189], v148 offset:51200
	ds_read_b128 v[190:193], v148 offset:52224
	ds_read_b128 v[194:197], v148 offset:53248
	ds_read_b128 v[198:201], v148 offset:54272
	ds_read_b128 v[202:205], v148 offset:55296
	ds_read_b128 v[206:209], v148 offset:56320
	global_load_lds_dwordx4 v2, s[98:99]
	s_add_i32 m0, s30, 0x2000
	s_add_u32 s20, s20, 0x80080
	s_addc_u32 s21, s21, 0
	s_add_i32 s30, s58, s11
	global_load_lds_dwordx4 v132, s[98:99]
	s_mov_b32 m0, s30
	s_nop 0
	global_load_lds_dwordx4 v2, s[20:21]
	s_add_i32 m0, s30, 0x2000
	s_nop 0
	global_load_lds_dwordx4 v132, s[20:21]
	s_mov_b32 m0, s18
	s_nop 0
	global_load_lds_dwordx4 v136, s[94:95]
	s_mov_b32 m0, s52
	s_nop 0
	global_load_lds_dwordx4 v134, s[94:95]
	s_waitcnt vmcnt(8)
	s_waitcnt lgkmcnt(0)
	s_barrier
	s_setprio 1
	s_waitcnt lgkmcnt(0)
	v_mfma_f32_16x16x32_bf16 v[64:67], v[142:145], v[178:181], v[64:67]
	v_mfma_f32_16x16x32_bf16 v[56:59], v[154:157], v[178:181], v[56:59]
	v_mfma_f32_16x16x32_bf16 v[48:51], v[142:145], v[186:189], v[48:51]
	v_mfma_f32_16x16x32_bf16 v[40:43], v[154:157], v[186:189], v[40:43]
	v_mfma_f32_16x16x32_bf16 v[32:35], v[142:145], v[194:197], v[32:35]
	v_mfma_f32_16x16x32_bf16 v[24:27], v[154:157], v[194:197], v[24:27]
	v_mfma_f32_16x16x32_bf16 v[16:19], v[142:145], v[202:205], v[16:19]
	v_mfma_f32_16x16x32_bf16 v[8:11], v[154:157], v[202:205], v[8:11]
	v_mfma_f32_16x16x32_bf16 v[64:67], v[150:153], v[182:185], v[64:67]
	v_mfma_f32_16x16x32_bf16 v[56:59], v[158:161], v[182:185], v[56:59]
	v_mfma_f32_16x16x32_bf16 v[48:51], v[150:153], v[190:193], v[48:51]
	v_mfma_f32_16x16x32_bf16 v[40:43], v[158:161], v[190:193], v[40:43]
	v_mfma_f32_16x16x32_bf16 v[32:35], v[150:153], v[198:201], v[32:35]
	v_mfma_f32_16x16x32_bf16 v[24:27], v[158:161], v[198:201], v[24:27]
	v_mfma_f32_16x16x32_bf16 v[16:19], v[150:153], v[206:209], v[16:19]
	v_mfma_f32_16x16x32_bf16 v[8:11], v[158:161], v[206:209], v[8:11]
	s_setprio 0
	s_setprio 1
	v_mfma_f32_16x16x32_bf16 v[60:63], v[162:165], v[178:181], v[60:63]
	v_mfma_f32_16x16x32_bf16 v[52:55], v[170:173], v[178:181], v[52:55]
	v_mfma_f32_16x16x32_bf16 v[44:47], v[162:165], v[186:189], v[44:47]
	v_mfma_f32_16x16x32_bf16 v[36:39], v[170:173], v[186:189], v[36:39]
	v_mfma_f32_16x16x32_bf16 v[28:31], v[162:165], v[194:197], v[28:31]
	v_mfma_f32_16x16x32_bf16 v[20:23], v[170:173], v[194:197], v[20:23]
	v_mfma_f32_16x16x32_bf16 v[12:15], v[162:165], v[202:205], v[12:15]
	v_mfma_f32_16x16x32_bf16 v[4:7], v[170:173], v[202:205], v[4:7]
	v_mfma_f32_16x16x32_bf16 v[60:63], v[166:169], v[182:185], v[60:63]
	v_mfma_f32_16x16x32_bf16 v[52:55], v[174:177], v[182:185], v[52:55]
	v_mfma_f32_16x16x32_bf16 v[44:47], v[166:169], v[190:193], v[44:47]
	v_mfma_f32_16x16x32_bf16 v[36:39], v[174:177], v[190:193], v[36:39]
	v_mfma_f32_16x16x32_bf16 v[28:31], v[166:169], v[198:201], v[28:31]
	v_mfma_f32_16x16x32_bf16 v[20:23], v[174:177], v[198:201], v[20:23]
	v_mfma_f32_16x16x32_bf16 v[12:15], v[166:169], v[206:209], v[12:15]
	v_mfma_f32_16x16x32_bf16 v[4:7], v[174:177], v[206:209], v[4:7]
	s_setprio 0
	s_barrier
	s_add_i32 s56, s56, 2
	s_add_u32 s33, s33, 0x100
	s_addc_u32 s55, s55, 0
	s_add_u32 s44, s44, 0x100
	s_addc_u32 s45, s45, 0
	s_cmp_gt_u32 s56, 29
	s_cbranch_scc0 .LBB0_2165
	s_and_b64 vcc, exec, s[22:23]
	s_cbranch_vccz .LBB0_2168
	s_barrier
